# in_proj epilogue rewritten by hand: destination (ZA / gate A / gate B) chosen once per column half with scalar compares instead of nested exec masks per store
# baseline (speedup 1.0000x reference)
.LBB0_327:
	v_mov_b32_e32 v64, v203
	s_lshl_b32 s2, s42, 8
	s_add_i32 s2, s2, s53
	s_lshl_b32 s3, s40, 8
	v_and_or_b32 v132, v64, 15, s2
	v_lshrrev_b32_e32 v64, 1, v64
	v_and_b32_e32 v130, 24, v64
	v_lshlrev_b32_e32 v130, 1, v130
	s_add_i32 s3, s3, s58
	s_add_i32 s2, s3, 0
	s_cmp_lt_u32 s2, 0x4a0
	s_cbranch_scc1 .Lie0_za
	s_cmp_lt_u32 s2, 0x8a0
	s_cbranch_scc1 .Lie0_ga
	s_cmp_lt_u32 s2, 0xca0
	s_cbranch_scc0 .Lie0_skip
	s_mov_b64 s[40:41], s[80:81]
	s_movk_i32 s42, 0x800
	s_sub_i32 s2, s2, 0x8a0
	s_branch .Lie0_go
.Lie0_ga:
	s_mov_b64 s[40:41], s[76:77]
	s_movk_i32 s42, 0x800
	s_sub_i32 s2, s2, 0x4a0
	s_branch .Lie0_go
.Lie0_za:
	s_mov_b64 s[40:41], s[56:57]
	s_mov_b32 s42, s69
.Lie0_go:
	s_lshl_b32 s2, s2, 1
	s_lshl_b32 s54, s42, 4
	s_mov_b32 s55, 0
	s_mul_i32 s64, s42, 80
	s_mov_b32 s65, 0
	v_mad_u64_u32 v[134:135], vcc, v132, s42, 0
	v_add_u32_e32 v64, s2, v130
	s_nop 0
	v_lshl_add_u64 v[134:135], s[40:41], 0, v[134:135]
	v_lshl_add_u64 v[134:135], v[64:65], 0, v[134:135]
	v_cvt_pk_bf16_f32 v126, v126, v127
	v_cvt_pk_bf16_f32 v127, v128, v129
	v_cvt_pk_bf16_f32 v128, v122, v123
	v_cvt_pk_bf16_f32 v129, v124, v125
	global_store_dwordx4 v[134:135], v[126:129], off
	v_lshl_add_u64 v[134:135], s[54:55], 0, v[134:135]
	v_cvt_pk_bf16_f32 v110, v110, v111
	v_cvt_pk_bf16_f32 v111, v112, v113
	v_cvt_pk_bf16_f32 v112, v106, v107
	v_cvt_pk_bf16_f32 v113, v108, v109
	global_store_dwordx4 v[134:135], v[110:113], off
	v_lshl_add_u64 v[134:135], s[54:55], 0, v[134:135]
	v_cvt_pk_bf16_f32 v94, v94, v95
	v_cvt_pk_bf16_f32 v95, v96, v97
	v_cvt_pk_bf16_f32 v96, v90, v91
	v_cvt_pk_bf16_f32 v97, v92, v93
	global_store_dwordx4 v[134:135], v[94:97], off
	v_lshl_add_u64 v[134:135], s[54:55], 0, v[134:135]
	v_cvt_pk_bf16_f32 v78, v78, v79
	v_cvt_pk_bf16_f32 v79, v80, v81
	v_cvt_pk_bf16_f32 v80, v74, v75
	v_cvt_pk_bf16_f32 v81, v76, v77
	global_store_dwordx4 v[134:135], v[78:81], off
	v_lshl_add_u64 v[134:135], s[64:65], 0, v[134:135]
	v_cvt_pk_bf16_f32 v60, v60, v61
	v_cvt_pk_bf16_f32 v61, v62, v63
	v_cvt_pk_bf16_f32 v62, v56, v57
	v_cvt_pk_bf16_f32 v63, v58, v59
	global_store_dwordx4 v[134:135], v[60:63], off
	v_lshl_add_u64 v[134:135], s[54:55], 0, v[134:135]
	v_cvt_pk_bf16_f32 v44, v44, v45
	v_cvt_pk_bf16_f32 v45, v46, v47
	v_cvt_pk_bf16_f32 v46, v40, v41
	v_cvt_pk_bf16_f32 v47, v42, v43
	global_store_dwordx4 v[134:135], v[44:47], off
	v_lshl_add_u64 v[134:135], s[54:55], 0, v[134:135]
	v_cvt_pk_bf16_f32 v28, v28, v29
	v_cvt_pk_bf16_f32 v29, v30, v31
	v_cvt_pk_bf16_f32 v30, v24, v25
	v_cvt_pk_bf16_f32 v31, v26, v27
	global_store_dwordx4 v[134:135], v[28:31], off
	v_lshl_add_u64 v[134:135], s[54:55], 0, v[134:135]
	v_cvt_pk_bf16_f32 v12, v12, v13
	v_cvt_pk_bf16_f32 v13, v14, v15
	v_cvt_pk_bf16_f32 v14, v8, v9
	v_cvt_pk_bf16_f32 v15, v10, v11
	global_store_dwordx4 v[134:135], v[12:15], off
.Lie0_skip:
	s_add_i32 s2, s3, 128
	s_cmp_lt_u32 s2, 0x4a0
	s_cbranch_scc1 .Lie1_za
	s_cmp_lt_u32 s2, 0x8a0
	s_cbranch_scc1 .Lie1_ga
	s_cmp_lt_u32 s2, 0xca0
	s_cbranch_scc0 .Lie1_skip
	s_mov_b64 s[40:41], s[80:81]
	s_movk_i32 s42, 0x800
	s_sub_i32 s2, s2, 0x8a0
	s_branch .Lie1_go

.Lie1_go:
	s_lshl_b32 s2, s2, 1
	s_lshl_b32 s54, s42, 4
	s_mov_b32 s55, 0
	s_mul_i32 s64, s42, 80
	s_mov_b32 s65, 0
	v_mad_u64_u32 v[134:135], vcc, v132, s42, 0
	v_add_u32_e32 v64, s2, v130
	s_nop 0
	v_lshl_add_u64 v[134:135], s[40:41], 0, v[134:135]
	v_lshl_add_u64 v[134:135], v[64:65], 0, v[134:135]
	v_cvt_pk_bf16_f32 v118, v118, v119
	v_cvt_pk_bf16_f32 v119, v120, v121
	v_cvt_pk_bf16_f32 v120, v114, v115
	v_cvt_pk_bf16_f32 v121, v116, v117
	global_store_dwordx4 v[134:135], v[118:121], off
	v_lshl_add_u64 v[134:135], s[54:55], 0, v[134:135]
	v_cvt_pk_bf16_f32 v102, v102, v103
	v_cvt_pk_bf16_f32 v103, v104, v105
	v_cvt_pk_bf16_f32 v104, v98, v99
	v_cvt_pk_bf16_f32 v105, v100, v101
	global_store_dwordx4 v[134:135], v[102:105], off
	v_lshl_add_u64 v[134:135], s[54:55], 0, v[134:135]
	v_cvt_pk_bf16_f32 v86, v86, v87
	v_cvt_pk_bf16_f32 v87, v88, v89
	v_cvt_pk_bf16_f32 v88, v82, v83
	v_cvt_pk_bf16_f32 v89, v84, v85
	global_store_dwordx4 v[134:135], v[86:89], off
	v_lshl_add_u64 v[134:135], s[54:55], 0, v[134:135]
	v_cvt_pk_bf16_f32 v70, v70, v71
	v_cvt_pk_bf16_f32 v71, v72, v73
	v_cvt_pk_bf16_f32 v72, v66, v67
	v_cvt_pk_bf16_f32 v73, v68, v69
	global_store_dwordx4 v[134:135], v[70:73], off
	v_lshl_add_u64 v[134:135], s[64:65], 0, v[134:135]
	v_cvt_pk_bf16_f32 v52, v52, v53
	v_cvt_pk_bf16_f32 v53, v54, v55
	v_cvt_pk_bf16_f32 v54, v48, v49
	v_cvt_pk_bf16_f32 v55, v50, v51
	global_store_dwordx4 v[134:135], v[52:55], off
	v_lshl_add_u64 v[134:135], s[54:55], 0, v[134:135]
	v_cvt_pk_bf16_f32 v36, v36, v37
	v_cvt_pk_bf16_f32 v37, v38, v39
	v_cvt_pk_bf16_f32 v38, v32, v33
	v_cvt_pk_bf16_f32 v39, v34, v35
	global_store_dwordx4 v[134:135], v[36:39], off
	v_lshl_add_u64 v[134:135], s[54:55], 0, v[134:135]
	v_cvt_pk_bf16_f32 v20, v20, v21
	v_cvt_pk_bf16_f32 v21, v22, v23
	v_cvt_pk_bf16_f32 v22, v16, v17
	v_cvt_pk_bf16_f32 v23, v18, v19
	global_store_dwordx4 v[134:135], v[20:23], off
	v_lshl_add_u64 v[134:135], s[54:55], 0, v[134:135]
	v_cvt_pk_bf16_f32 v4, v4, v5
	v_cvt_pk_bf16_f32 v5, v6, v7
	v_cvt_pk_bf16_f32 v6, v0, v1
	v_cvt_pk_bf16_f32 v7, v2, v3
	global_store_dwordx4 v[134:135], v[4:7], off
.Lie1_skip:
	s_andn2_b64 vcc, exec, s[84:85]
	s_mov_b64 s[2:3], -1
	s_cbranch_vccnz .LBB0_320
